# v6 + attention: next-tile K/V DMA issued piecewise in the QK MFMA shadow (scalar-base form), first V fragments fetched during QK, next tile's K fragments prefetched behind the closing barrier
# speedup vs baseline: 1.0185x; 1.0013x over previous
; #define LAS __attribute__((address_space(3)))
; #define SBAR() __builtin_amdgcn_sched_barrier(0)
; __device__ __forceinline__ int v_rd_base(int lane) { return ((lane & 3) << 3) | (((lane >> 2) & 3) << 6) | (((lane >> 4) & 1) << 5) | (((lane >> 5) & 1) << 8); }
; __device__ __forceinline__ void body(const bf16_t* __restrict__ Qb, const bf16_t* __restrict__ Kh, const bf16_t* __restrict__ Vh, bf16_t* __restrict__ Ob, int seq, char* lds) {
;     ...
;   float m_reg = -1e30f, l_reg = 0; f32x16 o[8] = {}; bf16x8 qr[8];
;   const bf16_t* Qw = Qb + (long)(wid * QBLK + r32) * LDQ + hi * 8;
; #pragma unroll
;   for (int d0 = 0; d0 < 8; ++d0) qr[d0] = *reinterpret_cast<const bf16x8*>(Qw + d0 * 16);
;   const int wu = __builtin_amdgcn_readfirstlane(wid);
;   int koff[2], voff[4];
; #pragma unroll
;   for (int q = 0; q < 2; ++q) { const int row = 4 * (wu * 2 + q) + (lane >> 4); koff[q] = row * LDK + ((((lane & 15) << 4) ^ ((row & 7) << 4)) >> 1); }
; #pragma unroll
;   for (int q = 0; q < 4; ++q) { const int s = 2 * (wu * 4 + q) + (lane >> 5), kk = (s >> 3) * 8 + ((lane & 31) >> 2), k = (kk & ~0xC) | ((kk & 4) << 1) | ((kk & 8) >> 1);
;     voff[q] = k * LDV + (s & 7) * 32 + (lane & 3) * 8; }
;   const int vb0 = (int)(uintptr_t)(LAS char*)V_lds + v_rd_base(lane);
;   LAS char* Vl = (LAS char*)V_lds; LAS char* Kl = (LAS char*)K_lds;
;     ...
;   const int NT = seq / KVBLK;
;   if (wu >= 4) __builtin_amdgcn_s_setprio(2);
;   STAGE(0, 0);
;   asm volatile("s_waitcnt vmcnt(0) lgkmcnt(0)" ::: "memory"); __builtin_amdgcn_s_barrier(); asm volatile("" ::: "memory");
;   for (int j = 0; j < NT; ++j) {
;     const int b = j & 1;
;     f32x16 p0, p1; float mn, al; bf16x8 pa0, pa1, pa2, pa3;
;     if (j + 1 < NT) STAGE(b ^ 1, (j + 1) * KVBLK);
;     SBAR(); qkt(p0, p1, K_lds + b * SK, qr, r32, hi);
.LBB0_615:
	s_mul_i32 s9, s25, 0x44
	s_or_b32 s10, s9, s7
	s_ashr_i32 s11, s10, 31
	s_lshl_b64 s[12:13], s[10:11], 17
	s_add_u32 s7, s4, s12
	s_addc_u32 s9, s5, s13
	s_add_u32 s10, s7, s8
	s_addc_u32 s11, s9, 0
	v_and_b32_e32 v6, 63, v1
	s_add_u32 s12, s14, s12
	v_lshlrev_b32_e32 v3, 4, v1
	v_and_b32_e32 v5, 48, v1
	s_movk_i32 s8, 0xf0
	s_addc_u32 s13, s15, s13
	s_lshl_b32 s7, s6, 3
	v_lshrrev_b32_e32 v2, 4, v6
	v_and_b32_e32 v4, 0xf0, v3
	v_bitop3_b32 v3, v3, v5, s8 bitop3:0x6c
	v_or_b32_e32 v2, s7, v2
	v_lshrrev_b32_e32 v3, 1, v3
	v_lshl_or_b32 v214, v2, 8, v3
	v_or_b32_e32 v2, 4, v2
	v_lshlrev_b32_e32 v3, 4, v2
	s_movk_i32 s8, 0x70
	v_bitop3_b32 v3, v3, v4, s8 bitop3:0x6c
	v_lshrrev_b32_e32 v3, 1, v3
	v_lshl_or_b32 v216, v2, 8, v3
	v_lshrrev_b32_e32 v2, 2, v231
	v_bitop3_b32 v2, s7, v229, v2 bitop3:0xc8
	v_lshrrev_b32_e32 v3, 1, v231
	s_lshl_b32 s7, s6, 2
	v_and_b32_e32 v3, 8, v3
	s_and_b32 s7, s7, 4
	v_or3_b32 v2, v3, v2, s7
	s_lshl_b32 s7, s6, 11
	v_lshlrev_b32_e32 v4, 3, v1
	s_add_i32 s7, s7, 16
	v_lshlrev_b32_e32 v2, 8, v2
	v_and_b32_e32 v3, 32, v1
	v_and_b32_e32 v4, 24, v4
	s_add_i32 s27, s7, 0x10000
	v_lshrrev_b32_e32 v8, 4, v220
	v_and_b32_e32 v9, 3, v8
	v_lshrrev_b32_e32 v8, 2, v8
	v_lshl_or_b32 v8, v8, 3, v9
	v_and_b32_e32 v9, 15, v220
	v_xor_b32_e32 v10, v9, v8
	v_and_b32_e32 v10, 15, v10
	v_lshlrev_b32_e32 v10, 3, v10
	v_lshl_or_b32 v214, v8, 8, v10
	v_or_b32_e32 v8, 4, v8
	v_xor_b32_e32 v10, v9, v8
	v_and_b32_e32 v10, 15, v10
	v_lshlrev_b32_e32 v10, 3, v10
	v_lshl_or_b32 v216, v8, 8, v10
	v_ashrrev_i32_e32 v215, 31, v214
	v_or3_b32 v218, v2, v3, v4
	v_lshl_add_u64 v[2:3], v[214:215], 1, s[10:11]
	s_mov_b32 m0, s27
	v_ashrrev_i32_e32 v217, 31, v216
	s_lshl_b32 s6, s6, 12
	global_load_lds_dwordx4 v[2:3], off
	v_lshl_add_u64 v[2:3], v[216:217], 1, s[10:11]
	s_add_i32 m0, s7, 0x10400
	s_add_i32 s28, s6, 16
	v_ashrrev_i32_e32 v219, 31, v218
	global_load_lds_dwordx4 v[2:3], off
	v_lshl_add_u64 v[2:3], v[218:219], 1, s[12:13]
	s_mov_b32 m0, s28
	v_lshl_add_u64 v[4:5], v[2:3], 0, s[36:37]
	global_load_lds_dwordx4 v[2:3], off
	s_add_i32 m0, s28, 0x400
	v_and_b32_e32 v1, 0x3fffffc0, v1
	global_load_lds_dwordx4 v[4:5], off
	v_lshl_add_u64 v[4:5], v[2:3], 0, s[40:41]
	s_add_i32 m0, s28, 0x800
	v_lshl_add_u64 v[2:3], v[2:3], 0, s[46:47]
	global_load_lds_dwordx4 v[4:5], off
	s_add_i32 m0, s28, 0xc00
	s_add_i32 s6, 16, 0x18000
	global_load_lds_dwordx4 v[2:3], off
	v_lshlrev_b32_e32 v4, 4, v231
	v_lshl_add_u32 v211, v1, 2, s6
	v_and_b32_e32 v5, 0x70, v4
	s_movk_i32 s6, 0x60
	v_lshlrev_b32_e32 v3, 1, v6
	v_bitop3_b32 v236, v212, v5, s6 bitop3:0x36
	s_movk_i32 s6, 0xa0
	v_lshlrev_b32_e32 v1, 3, v6
	v_lshlrev_b32_e32 v2, 4, v6
	v_and_b32_e32 v3, 32, v3
	v_bitop3_b32 v233, v212, v4, s8 bitop3:0x78
	v_bitop3_b32 v239, v212, v5, s6 bitop3:0x36
	s_movk_i32 s6, 0xc0
	s_movk_i32 s8, 0x118
	v_and_b32_e32 v2, 0xc0, v2
	v_bitop3_b32 v240, v212, v5, s6 bitop3:0x36
	s_movk_i32 s6, 0xe0
	v_and_or_b32 v1, v1, s8, v3
	v_mov_b32_e32 v14, v0
	v_mov_b32_e32 v15, v0
	s_waitcnt vmcnt(0) lgkmcnt(0)
	s_barrier
	v_bitop3_b32 v234, v212, v5, 32 bitop3:0x36
	v_bitop3_b32 v235, v212, v5, 64 bitop3:0x36
	v_bitop3_b32 v238, v212, v5, s82 bitop3:0x36
	v_bitop3_b32 v241, v212, v5, s6 bitop3:0x36
	v_cmp_gt_u32_e64 s[6:7], 32, v6
	v_add3_u32 v242, v2, 16, v1
	v_mov_b32_e32 v1, v0
	v_mov_b32_e32 v2, v0
	v_mov_b32_e32 v3, v0
	v_mov_b32_e32 v4, v0
	v_mov_b32_e32 v5, v0
	v_mov_b32_e32 v6, v0
	v_mov_b32_e32 v7, v0
	v_mov_b32_e32 v8, v0
	v_mov_b32_e32 v9, v0
	v_mov_b32_e32 v10, v0
	v_mov_b32_e32 v11, v0
	v_mov_b32_e32 v12, v0
	v_mov_b32_e32 v13, v0
	v_mov_b64_e32 v[128:129], v[14:15]
	v_mov_b64_e32 v[112:113], v[14:15]
	v_mov_b64_e32 v[96:97], v[14:15]
	v_mov_b64_e32 v[80:81], v[14:15]
	v_mov_b64_e32 v[64:65], v[14:15]
	v_mov_b64_e32 v[48:49], v[14:15]
	v_mov_b64_e32 v[32:33], v[14:15]
	v_mov_b64_e32 v[126:127], v[12:13]
	v_mov_b64_e32 v[124:125], v[10:11]
	v_mov_b64_e32 v[122:123], v[8:9]
	v_mov_b64_e32 v[120:121], v[6:7]
	v_mov_b64_e32 v[118:119], v[4:5]
	v_mov_b64_e32 v[116:117], v[2:3]
	v_mov_b64_e32 v[114:115], v[0:1]
	v_mov_b64_e32 v[110:111], v[12:13]
	v_mov_b64_e32 v[108:109], v[10:11]
	v_mov_b64_e32 v[106:107], v[8:9]
	v_mov_b64_e32 v[104:105], v[6:7]
	v_mov_b64_e32 v[102:103], v[4:5]
	v_mov_b64_e32 v[100:101], v[2:3]
	v_mov_b64_e32 v[98:99], v[0:1]
	v_mov_b64_e32 v[94:95], v[12:13]
	v_mov_b64_e32 v[92:93], v[10:11]
	v_mov_b64_e32 v[90:91], v[8:9]
	v_mov_b64_e32 v[88:89], v[6:7]
	v_mov_b64_e32 v[86:87], v[4:5]
	v_mov_b64_e32 v[84:85], v[2:3]
	v_mov_b64_e32 v[82:83], v[0:1]
	v_mov_b64_e32 v[78:79], v[12:13]
	v_mov_b64_e32 v[76:77], v[10:11]
	v_mov_b64_e32 v[74:75], v[8:9]
	v_mov_b64_e32 v[72:73], v[6:7]
	v_mov_b64_e32 v[70:71], v[4:5]
	v_mov_b64_e32 v[68:69], v[2:3]
	v_mov_b64_e32 v[66:67], v[0:1]
	v_mov_b64_e32 v[62:63], v[12:13]
	v_mov_b64_e32 v[60:61], v[10:11]
	v_mov_b64_e32 v[58:59], v[8:9]
	v_mov_b64_e32 v[56:57], v[6:7]
	v_mov_b64_e32 v[54:55], v[4:5]
	v_mov_b64_e32 v[52:53], v[2:3]
	v_mov_b64_e32 v[50:51], v[0:1]
	v_mov_b64_e32 v[46:47], v[12:13]
	v_mov_b64_e32 v[44:45], v[10:11]
	v_mov_b64_e32 v[42:43], v[8:9]
	v_mov_b64_e32 v[40:41], v[6:7]
	v_mov_b64_e32 v[38:39], v[4:5]
	v_mov_b64_e32 v[36:37], v[2:3]
	v_mov_b64_e32 v[34:35], v[0:1]
	v_mov_b64_e32 v[30:31], v[12:13]
	v_mov_b64_e32 v[28:29], v[10:11]
	v_mov_b64_e32 v[26:27], v[8:9]
	v_mov_b64_e32 v[24:25], v[6:7]
	v_mov_b64_e32 v[22:23], v[4:5]
	v_mov_b64_e32 v[20:21], v[2:3]
	v_mov_b64_e32 v[18:19], v[0:1]
	v_mov_b64_e32 v[16:17], v[14:15]
	v_lshlrev_b32_e32 v213, 8, v231
	v_lshl_add_u32 v237, v231, 2, v211
	s_mov_b32 s29, 0
	v_mov_b32_e32 v244, 0
	v_mov_b32_e32 v243, 0xf149f2ca
	s_movk_i32 s33, 0x4000
	v_mov_b64_e32 v[14:15], v[12:13]
	v_mov_b64_e32 v[12:13], v[10:11]
	v_mov_b64_e32 v[10:11], v[8:9]
	v_mov_b64_e32 v[8:9], v[6:7]
	v_mov_b64_e32 v[6:7], v[4:5]
	v_mov_b64_e32 v[4:5], v[2:3]
	v_mov_b64_e32 v[2:3], v[0:1]
	v_lshlrev_b32_e32 v233, 4, v231
	v_and_b32_e32 v233, 0xf0, v233
	v_xor_b32_e32 v233, v233, v212
	v_xor_b32_e32 v234, 32, v233
	v_xor_b32_e32 v235, 64, v233
	v_xor_b32_e32 v236, 0x60, v233
	v_xor_b32_e32 v238, 0x80, v233
	v_xor_b32_e32 v239, 0xa0, v233
	v_xor_b32_e32 v240, 0xc0, v233
	v_xor_b32_e32 v241, 0xe0, v233
	s_waitcnt vmcnt(0)
	v_lshlrev_b32_e32 v214, 1, v214
	v_lshlrev_b32_e32 v215, 1, v216
	v_lshlrev_b32_e32 v216, 1, v218
	v_add_u32_e32 v217, 0x80, v216
	v_add_u32_e32 v218, 0x100, v216
	v_add_u32_e32 v219, 0x180, v216
	s_mov_b32 s8, 0x10010
	v_add3_u32 v1, s8, v233, v213
	ds_read_b128 v[194:197], v1
	ds_read_b128 v[198:201], v1 offset:8192
	v_add3_u32 v1, s8, v234, v213
	ds_read_b128 v[202:205], v1
	ds_read_b128 v[206:209], v1 offset:8192
	v_add3_u32 v1, s8, v235, v213
	ds_read_b128 v[246:249], v1
	ds_read_b128 v[252:255], v1 offset:8192
; #define SBAR() __builtin_amdgcn_sched_barrier(0)
; __device__ __forceinline__ void partialSM(f32x16& p0, f32x16& p1, float& m_reg, float& mn, float& alpha) {
;   constexpr float C = SCALE * 1.4426950408889634f;
;   float pmax = p0[0];
; #pragma unroll
;   for (int r = 1; r < 16; ++r) pmax = fmaxf(pmax, p0[r]);
; #pragma unroll
;   for (int r = 0; r < 16; ++r) pmax = fmaxf(pmax, p1[r]);
;   { auto rr = __builtin_amdgcn_permlane32_swap(__float_as_uint(pmax), __float_as_uint(pmax), false, false);
;     pmax = fmaxf(__uint_as_float(rr[0]), __uint_as_float(rr[1])); }
;   if (__builtin_expect(__all(pmax - m_reg <= THR / SCALE), 1)) { mn = m_reg; alpha = 1.f; }
;   else { mn = fmaxf(m_reg, pmax); alpha = __builtin_amdgcn_exp2f((m_reg - mn) * C); m_reg = mn; }
; __device__ __forceinline__ void body(const bf16_t* __restrict__ Qb, const bf16_t* __restrict__ Kh, const bf16_t* __restrict__ Vh, bf16_t* __restrict__ Ob, int seq, char* lds) {
;     ...
;   const int NT = seq / KVBLK;
;   if (wu >= 4) __builtin_amdgcn_s_setprio(2);
;   STAGE(0, 0);
;   asm volatile("s_waitcnt vmcnt(0) lgkmcnt(0)" ::: "memory"); __builtin_amdgcn_s_barrier(); asm volatile("" ::: "memory");
;   for (int j = 0; j < NT; ++j) {
;     const int b = j & 1;
;     f32x16 p0, p1; float mn, al; bf16x8 pa0, pa1, pa2, pa3;
;     if (j + 1 < NT) STAGE(b ^ 1, (j + 1) * KVBLK);
;     SBAR(); qkt(p0, p1, K_lds + b * SK, qr, r32, hi);
;     partialSM(p0, p1, m_reg, mn, al);
.LBB0_616:
	s_and_b32 s34, s29, 1
	s_add_i32 s29, s29, 1
	s_lshl_b32 s30, s34, 14
	s_add_i32 s8, s30, 0x10010
	s_waitcnt lgkmcnt(4)
	v_mfma_f32_32x32x16_bf16 v[146:161], v[194:197], v[162:165], 0
	v_mfma_f32_32x32x16_bf16 v[130:145], v[198:201], v[162:165], 0
	v_add3_u32 v1, s8, v236, v213
	ds_read_b128 v[194:197], v1
	ds_read_b128 v[198:201], v1 offset:8192
	s_add_i32 s44, s24, -1
	s_min_u32 s44, s44, s29
	s_lshr_b32 s42, s44, 2
	s_lshl_b32 s42, s42, 19
	s_and_b32 s43, s44, 3
	s_lshl_b32 s43, s43, 15
	s_add_u32 s44, s42, s43
	s_add_u32 s42, s10, s44
	s_addc_u32 s43, s11, 0
	s_add_u32 s100, s12, s44
	s_addc_u32 s101, s13, 0
	s_xor_b32 s39, s30, 0x4000
	s_add_i32 s39, s27, s39
	s_lshl_b32 s9, s34, 15
	s_xor_b32 s9, s9, 0x8000
	s_add_i32 s9, s28, s9
	v_lshl_add_u32 v251, s34, 15, v242
	s_mov_b32 m0, s39
	s_waitcnt lgkmcnt(4)
	v_mfma_f32_32x32x16_bf16 v[146:161], v[202:205], v[166:169], v[146:161]
	v_mfma_f32_32x32x16_bf16 v[130:145], v[206:209], v[166:169], v[130:145]
	global_load_lds_dwordx4 v214, s[42:43]
	v_add3_u32 v1, s8, v238, v213
	ds_read_b128 v[202:205], v1
	ds_read_b128 v[206:209], v1 offset:8192
	s_add_i32 m0, s39, 0x400
	s_waitcnt lgkmcnt(4)
	v_mfma_f32_32x32x16_bf16 v[146:161], v[246:249], v[170:173], v[146:161]
	v_mfma_f32_32x32x16_bf16 v[130:145], v[252:255], v[170:173], v[130:145]
	global_load_lds_dwordx4 v215, s[42:43]
	v_add3_u32 v1, s8, v239, v213
	ds_read_b128 v[246:249], v1
	ds_read_b128 v[252:255], v1 offset:8192
	s_mov_b32 m0, s9
	s_waitcnt lgkmcnt(4)
	v_mfma_f32_32x32x16_bf16 v[146:161], v[194:197], v[174:177], v[146:161]
	v_mfma_f32_32x32x16_bf16 v[130:145], v[198:201], v[174:177], v[130:145]
	global_load_lds_dwordx4 v216, s[100:101]
	v_add3_u32 v1, s8, v240, v213
	ds_read_b128 v[194:197], v1
	ds_read_b128 v[198:201], v1 offset:8192
	s_add_i32 m0, s9, 0x400
	s_waitcnt lgkmcnt(4)
	v_mfma_f32_32x32x16_bf16 v[146:161], v[202:205], v[178:181], v[146:161]
	v_mfma_f32_32x32x16_bf16 v[130:145], v[206:209], v[178:181], v[130:145]
	global_load_lds_dwordx4 v217, s[100:101]
	v_add3_u32 v1, s8, v241, v213
	ds_read_b128 v[202:205], v1
	ds_read_b128 v[206:209], v1 offset:8192
	s_add_i32 m0, s9, 0x800
	s_waitcnt lgkmcnt(4)
	v_mfma_f32_32x32x16_bf16 v[146:161], v[246:249], v[182:185], v[146:161]
	v_mfma_f32_32x32x16_bf16 v[130:145], v[252:255], v[182:185], v[130:145]
	global_load_lds_dwordx4 v218, s[100:101]
	s_add_i32 m0, s9, 0xc00
	ds_read_b64_tr_b16 v[246:247], v251 offset:0
	ds_read_b64_tr_b16 v[248:249], v251 offset:4096
	ds_read_b64_tr_b16 v[252:253], v251 offset:8192
	ds_read_b64_tr_b16 v[254:255], v251 offset:12288
	s_waitcnt lgkmcnt(6)
	v_mfma_f32_32x32x16_bf16 v[146:161], v[194:197], v[186:189], v[146:161]
	v_mfma_f32_32x32x16_bf16 v[130:145], v[198:201], v[186:189], v[130:145]
	global_load_lds_dwordx4 v219, s[100:101]
	s_mov_b32 s8, 0x42b504f3
	s_waitcnt lgkmcnt(4)
	v_mfma_f32_32x32x16_bf16 v[146:161], v[202:205], v[190:193], v[146:161]
	v_mfma_f32_32x32x16_bf16 v[130:145], v[206:209], v[190:193], v[130:145]
	s_nop 10
	v_max_f32_e32 v1, v147, v147
	v_max_f32_e32 v194, v146, v146
	v_max_f32_e32 v1, v194, v1
	v_max3_f32 v1, v1, v148, v149
	v_max3_f32 v1, v1, v150, v151
	v_max3_f32 v1, v1, v152, v153
	v_max3_f32 v1, v1, v154, v155
	v_max3_f32 v1, v1, v156, v157
	v_max3_f32 v1, v1, v158, v159
	v_max3_f32 v1, v1, v160, v161
	v_max3_f32 v1, v1, v130, v131
	v_max3_f32 v1, v1, v132, v133
	v_max3_f32 v1, v1, v134, v135
	v_max3_f32 v1, v1, v136, v137
	v_max3_f32 v1, v1, v138, v139
	v_max3_f32 v1, v1, v140, v141
	v_max3_f32 v1, v1, v142, v143
	v_max3_f32 v1, v1, v144, v145
	v_mov_b32_e32 v194, v1
	s_nop 1
	v_permlane32_swap_b32_e32 v1, v194
	v_max_f32_e32 v194, v194, v194
	v_max_f32_e32 v1, v1, v1
	v_max_f32_e32 v1, v1, v194
	v_sub_f32_e32 v194, v1, v243
	v_cmp_ge_f32_e32 vcc, s8, v194
	v_max_f32_e32 v194, v243, v243
	v_max_f32_e32 v245, v194, v1
	v_sub_f32_e32 v1, v243, v245
	v_mul_f32_e32 v1, 0x3e0293ee, v1
	v_exp_f32_e32 v1, v1
	s_cmp_eq_u64 vcc, exec
	s_cselect_b64 s[8:9], -1, 0
	v_cndmask_b32_e64 v1, v1, 1.0, s[8:9]
	v_cmp_gt_f32_e32 vcc, 1.0, v1
	s_cbranch_vccz .LBB0_624
	s_and_saveexec_b64 s[54:55], s[6:7]
	ds_write_b32 v237, v1 offset:128
	s_or_b64 exec, exec, s[54:55]
	s_waitcnt lgkmcnt(0)
	v_add_u32_e32 v194, v211, v212
	ds_read_b128 v[206:209], v194 offset:224
	ds_read_b128 v[202:205], v194 offset:192
	ds_read_b128 v[198:201], v194 offset:160
	ds_read_b128 v[194:197], v194 offset:128
	s_waitcnt lgkmcnt(0)
; __device__ __forceinline__ int crow(int r, int hi) { return (r & 3) + 8 * (r >> 2) + 4 * hi; }
; __device__ __forceinline__ void partialSM(f32x16& p0, f32x16& p1, float& m_reg, float& mn, float& alpha) {
;     ...
;   float mnC = -mn * C;
; #pragma unroll
;   for (int r = 0; r < 16; ++r) p0[r] = fmaf(p0[r], C, mnC);
; #pragma unroll
;   for (int r = 0; r < 16; ++r) p1[r] = fmaf(p1[r], C, mnC);
; #pragma unroll
;   for (int r = 0; r < 16; ++r) p0[r] = __builtin_amdgcn_exp2f(p0[r]);
; }
; __device__ __forceinline__ void finishSM(f32x16& p0, f32x16& p1, float alpha, float& l_reg, bf16x8& pa0, bf16x8& pa1, bf16x8& pa2, bf16x8& pa3) {
; #pragma unroll
;   for (int r = 0; r < 16; ++r) p1[r] = __builtin_amdgcn_exp2f(p1[r]);
;   float ps = 0;
; #pragma unroll
;   for (int r = 0; r < 16; ++r) ps += p0[r];
; #pragma unroll
;   for (int r = 0; r < 16; ++r) ps += p1[r];
;   { auto rr = __builtin_amdgcn_permlane32_swap(__float_as_uint(ps), __float_as_uint(ps), false, false);
;     ps = __uint_as_float(rr[0]) + __uint_as_float(rr[1]); }
;   l_reg = l_reg * alpha + ps;
; __device__ __forceinline__ void body(const bf16_t* __restrict__ Qb, const bf16_t* __restrict__ Kh, const bf16_t* __restrict__ Vh, bf16_t* __restrict__ Ob, int seq, char* lds) {
;     ...
;     if (__any(al < 1.f)) { if (hi == 0) al_l[r32] = al; asm volatile("s_waitcnt lgkmcnt(0)" ::: "memory");
; #pragma unroll
;       for (int d = 0; d < 8; ++d)
; #pragma unroll
;         for (int r = 0; r < 16; ++r) o[d][r] *= al_l[crow(r, hi)]; }
	v_pk_mul_f32 v[126:127], v[126:127], v[206:207]
	v_pk_mul_f32 v[122:123], v[122:123], v[202:203]
	v_pk_mul_f32 v[118:119], v[118:119], v[198:199]
	v_pk_mul_f32 v[128:129], v[128:129], v[208:209]
	v_pk_mul_f32 v[124:125], v[124:125], v[204:205]
	v_pk_mul_f32 v[120:121], v[120:121], v[200:201]
	v_pk_mul_f32 v[116:117], v[116:117], v[196:197]
	v_pk_mul_f32 v[114:115], v[114:115], v[194:195]
	v_pk_mul_f32 v[110:111], v[110:111], v[206:207]
	v_pk_mul_f32 v[106:107], v[106:107], v[202:203]
	v_pk_mul_f32 v[102:103], v[102:103], v[198:199]
	v_pk_mul_f32 v[112:113], v[112:113], v[208:209]
	v_pk_mul_f32 v[108:109], v[108:109], v[204:205]
	v_pk_mul_f32 v[104:105], v[104:105], v[200:201]
	v_pk_mul_f32 v[100:101], v[100:101], v[196:197]
	v_pk_mul_f32 v[98:99], v[98:99], v[194:195]
	v_pk_mul_f32 v[94:95], v[94:95], v[206:207]
	v_pk_mul_f32 v[90:91], v[90:91], v[202:203]
	v_pk_mul_f32 v[86:87], v[86:87], v[198:199]
	v_pk_mul_f32 v[96:97], v[96:97], v[208:209]
	v_pk_mul_f32 v[92:93], v[92:93], v[204:205]
	v_pk_mul_f32 v[88:89], v[88:89], v[200:201]
	v_pk_mul_f32 v[84:85], v[84:85], v[196:197]
	v_pk_mul_f32 v[82:83], v[82:83], v[194:195]
	v_pk_mul_f32 v[78:79], v[78:79], v[206:207]
	v_pk_mul_f32 v[74:75], v[74:75], v[202:203]
	v_pk_mul_f32 v[70:71], v[70:71], v[198:199]
	v_pk_mul_f32 v[80:81], v[80:81], v[208:209]
	v_pk_mul_f32 v[76:77], v[76:77], v[204:205]
	v_pk_mul_f32 v[72:73], v[72:73], v[200:201]
	v_pk_mul_f32 v[68:69], v[68:69], v[196:197]
	v_pk_mul_f32 v[66:67], v[66:67], v[194:195]
	v_pk_mul_f32 v[62:63], v[62:63], v[206:207]
	v_pk_mul_f32 v[58:59], v[58:59], v[202:203]
	v_pk_mul_f32 v[54:55], v[54:55], v[198:199]
	v_pk_mul_f32 v[64:65], v[64:65], v[208:209]
	v_pk_mul_f32 v[60:61], v[60:61], v[204:205]
	v_pk_mul_f32 v[56:57], v[56:57], v[200:201]
	v_pk_mul_f32 v[52:53], v[52:53], v[196:197]
	v_pk_mul_f32 v[50:51], v[50:51], v[194:195]
	v_pk_mul_f32 v[46:47], v[46:47], v[206:207]
	v_pk_mul_f32 v[42:43], v[42:43], v[202:203]
	v_pk_mul_f32 v[38:39], v[38:39], v[198:199]
	v_pk_mul_f32 v[48:49], v[48:49], v[208:209]
	v_pk_mul_f32 v[44:45], v[44:45], v[204:205]
	v_pk_mul_f32 v[40:41], v[40:41], v[200:201]
	v_pk_mul_f32 v[36:37], v[36:37], v[196:197]
	v_pk_mul_f32 v[34:35], v[34:35], v[194:195]
	v_pk_mul_f32 v[30:31], v[30:31], v[206:207]
	v_pk_mul_f32 v[26:27], v[26:27], v[202:203]
	v_pk_mul_f32 v[22:23], v[22:23], v[198:199]
	v_pk_mul_f32 v[32:33], v[32:33], v[208:209]
	v_pk_mul_f32 v[28:29], v[28:29], v[204:205]
	v_pk_mul_f32 v[24:25], v[24:25], v[200:201]
	v_pk_mul_f32 v[20:21], v[20:21], v[196:197]
	v_pk_mul_f32 v[18:19], v[18:19], v[194:195]
	v_pk_mul_f32 v[14:15], v[14:15], v[206:207]
	v_pk_mul_f32 v[10:11], v[10:11], v[202:203]
	v_pk_mul_f32 v[6:7], v[6:7], v[198:199]
	v_pk_mul_f32 v[16:17], v[16:17], v[208:209]
	v_pk_mul_f32 v[12:13], v[12:13], v[204:205]
	v_pk_mul_f32 v[8:9], v[8:9], v[200:201]
	v_pk_mul_f32 v[4:5], v[4:5], v[196:197]
	v_pk_mul_f32 v[2:3], v[2:3], v[194:195]
.LBB0_624:
	v_cndmask_b32_e64 v243, v245, v243, s[8:9]
	v_mul_f32_e32 v194, 0xbe0293ee, v243
	v_fmamk_f32 v146, v146, 0x3e0293ee, v194
	v_fmamk_f32 v147, v147, 0x3e0293ee, v194
	v_fmamk_f32 v148, v148, 0x3e0293ee, v194
	v_fmamk_f32 v149, v149, 0x3e0293ee, v194
	v_fmamk_f32 v150, v150, 0x3e0293ee, v194
	v_fmamk_f32 v151, v151, 0x3e0293ee, v194
	v_fmamk_f32 v152, v152, 0x3e0293ee, v194
	v_fmamk_f32 v153, v153, 0x3e0293ee, v194
	v_fmamk_f32 v154, v154, 0x3e0293ee, v194
	v_fmamk_f32 v155, v155, 0x3e0293ee, v194
	v_fmamk_f32 v156, v156, 0x3e0293ee, v194
	v_fmamk_f32 v157, v157, 0x3e0293ee, v194
	v_fmamk_f32 v158, v158, 0x3e0293ee, v194
	v_fmamk_f32 v159, v159, 0x3e0293ee, v194
	v_fmamk_f32 v160, v160, 0x3e0293ee, v194
	v_fmamk_f32 v161, v161, 0x3e0293ee, v194
	v_fmamk_f32 v130, v130, 0x3e0293ee, v194
	v_fmamk_f32 v131, v131, 0x3e0293ee, v194
	v_fmamk_f32 v132, v132, 0x3e0293ee, v194
	v_fmamk_f32 v133, v133, 0x3e0293ee, v194
	v_fmamk_f32 v134, v134, 0x3e0293ee, v194
	v_fmamk_f32 v135, v135, 0x3e0293ee, v194
	v_fmamk_f32 v136, v136, 0x3e0293ee, v194
	v_fmamk_f32 v137, v137, 0x3e0293ee, v194
	v_fmamk_f32 v138, v138, 0x3e0293ee, v194
	v_fmamk_f32 v139, v139, 0x3e0293ee, v194
	v_fmamk_f32 v140, v140, 0x3e0293ee, v194
	v_fmamk_f32 v141, v141, 0x3e0293ee, v194
	v_fmamk_f32 v142, v142, 0x3e0293ee, v194
	v_fmamk_f32 v143, v143, 0x3e0293ee, v194
	v_fmamk_f32 v144, v144, 0x3e0293ee, v194
	v_fmac_f32_e32 v194, 0x3e0293ee, v145
	v_exp_f32_e32 v145, v146
	v_exp_f32_e32 v147, v147
	v_exp_f32_e32 v148, v148
	v_exp_f32_e32 v149, v149
	v_exp_f32_e32 v150, v150
	v_exp_f32_e32 v195, v130
	v_add_f32_e32 v130, 0, v145
	v_exp_f32_e32 v151, v151
	v_add_f32_e32 v130, v147, v130
	v_exp_f32_e32 v152, v152
	v_add_f32_e32 v130, v148, v130
	v_exp_f32_e32 v153, v153
	v_add_f32_e32 v130, v149, v130
	v_exp_f32_e32 v154, v154
	v_add_f32_e32 v130, v150, v130
	v_exp_f32_e32 v155, v155
	v_add_f32_e32 v130, v151, v130
	v_exp_f32_e32 v156, v156
	v_add_f32_e32 v130, v152, v130
	v_exp_f32_e32 v157, v157
	v_add_f32_e32 v130, v153, v130
	v_exp_f32_e32 v158, v158
	v_add_f32_e32 v130, v154, v130
	v_exp_f32_e32 v159, v159
	v_add_f32_e32 v130, v155, v130
	v_exp_f32_e32 v160, v160
	v_add_f32_e32 v130, v156, v130
	v_exp_f32_e32 v161, v161
	v_add_f32_e32 v130, v157, v130
	v_add_f32_e32 v130, v158, v130
	v_exp_f32_e32 v196, v131
	v_add_f32_e32 v130, v159, v130
	v_exp_f32_e32 v197, v132
	v_add_f32_e32 v130, v160, v130
	v_exp_f32_e32 v198, v133
	v_add_f32_e32 v130, v161, v130
	v_exp_f32_e32 v199, v134
	v_add_f32_e32 v130, v195, v130
	v_exp_f32_e32 v200, v135
	v_add_f32_e32 v130, v196, v130
	v_exp_f32_e32 v201, v136
	v_add_f32_e32 v130, v197, v130
	v_exp_f32_e32 v202, v137
	v_add_f32_e32 v130, v198, v130
	v_exp_f32_e32 v203, v138
; #define SBAR() __builtin_amdgcn_sched_barrier(0)
; #define STEP(D, CUR, NXT) v_load<D + 1>(NXT, vb); asm volatile("s_waitcnt lgkmcnt(8)" ::: "memory"); SBAR(); pv_mma(o[D], CUR, pa0, pa1, pa2, pa3); SBAR();
; __device__ __forceinline__ void finishSM(f32x16& p0, f32x16& p1, float alpha, float& l_reg, bf16x8& pa0, bf16x8& pa1, bf16x8& pa2, bf16x8& pa3) {
; #pragma unroll
;   for (int r = 0; r < 16; ++r) p1[r] = __builtin_amdgcn_exp2f(p1[r]);
;   float ps = 0;
; #pragma unroll
;   for (int r = 0; r < 16; ++r) ps += p0[r];
; #pragma unroll
;   for (int r = 0; r < 16; ++r) ps += p1[r];
;   { auto rr = __builtin_amdgcn_permlane32_swap(__float_as_uint(ps), __float_as_uint(ps), false, false);
;     ps = __uint_as_float(rr[0]) + __uint_as_float(rr[1]); }
;   l_reg = l_reg * alpha + ps;
;     ...
;   PK4(p0, 0, pa0); PK4(p0, 8, pa1); PK4(p1, 0, pa2); PK4(p1, 8, pa3);
; __device__ __forceinline__ void pv_mma(f32x16& od, const VFrag& f, bf16x8 pa0, bf16x8 pa1, bf16x8 pa2, bf16x8 pa3) {
;     ...
;   od = __builtin_amdgcn_mfma_f32_32x32x16_bf16(pa0, PK(f.l0, f.h0), od, 0, 0, 0);
;   od = __builtin_amdgcn_mfma_f32_32x32x16_bf16(pa1, PK(f.l1, f.h1), od, 0, 0, 0);
;   od = __builtin_amdgcn_mfma_f32_32x32x16_bf16(pa2, PK(f.l2, f.h2), od, 0, 0, 0);
;   od = __builtin_amdgcn_mfma_f32_32x32x16_bf16(pa3, PK(f.l3, f.h3), od, 0, 0, 0);
;     ...
; }
; __device__ __forceinline__ void pv_all(f32x16* o, int vb, bf16x8 pa0, bf16x8 pa1, bf16x8 pa2, bf16x8 pa3) {
;   VFrag fa, fb;
;   v_load<0>(fa, vb);
;     ...
;   STEP(0, fa, fb) STEP(1, fb, fa) STEP(2, fa, fb) STEP(3, fb, fa) STEP(4, fa, fb) STEP(5, fb, fa) STEP(6, fa, fb)
;     ...
;   asm volatile("s_waitcnt lgkmcnt(0)" ::: "memory"); SBAR(); pv_mma(o[7], fb, pa0, pa1, pa2, pa3);
; }
	v_add_f32_e32 v130, v199, v130
	v_exp_f32_e32 v204, v139
	v_add_f32_e32 v130, v200, v130
	v_exp_f32_e32 v205, v140
	v_add_f32_e32 v130, v201, v130
	v_exp_f32_e32 v206, v141
	v_add_f32_e32 v130, v202, v130
	v_exp_f32_e32 v207, v142
	v_add_f32_e32 v130, v203, v130
	v_exp_f32_e32 v208, v143
	v_add_f32_e32 v130, v204, v130
	v_exp_f32_e32 v209, v144
	v_add_f32_e32 v130, v205, v130
	v_exp_f32_e32 v194, v194
	v_add_f32_e32 v130, v206, v130
	v_add_f32_e32 v130, v207, v130
	v_add_f32_e32 v130, v208, v130
	v_add_f32_e32 v130, v209, v130
	v_add_f32_e32 v130, v194, v130
	v_mov_b32_e32 v131, v130
	s_nop 1
	v_permlane32_swap_b32_e32 v130, v131
	v_add_f32_e32 v146, v130, v131
	v_fmac_f32_e32 v146, v244, v1
	v_cvt_pk_bf16_f32 v130, v145, v147
	v_cvt_pk_bf16_f32 v131, v148, v149
	v_cvt_pk_bf16_f32 v132, v150, v151
	v_cvt_pk_bf16_f32 v133, v152, v153
	v_cvt_pk_bf16_f32 v134, v154, v155
	v_cvt_pk_bf16_f32 v135, v156, v157
	v_cvt_pk_bf16_f32 v136, v158, v159
	v_cvt_pk_bf16_f32 v137, v160, v161
	v_cvt_pk_bf16_f32 v138, v195, v196
	v_cvt_pk_bf16_f32 v139, v197, v198
	v_cvt_pk_bf16_f32 v140, v199, v200
	v_cvt_pk_bf16_f32 v141, v201, v202
	v_cvt_pk_bf16_f32 v142, v203, v204
	v_cvt_pk_bf16_f32 v143, v205, v206
	v_cvt_pk_bf16_f32 v144, v207, v208
	v_cvt_pk_bf16_f32 v145, v209, v194
	s_nop 0
	v_permlane32_swap_b32_e32 v130, v132
	v_permlane32_swap_b32_e32 v131, v133
	v_permlane32_swap_b32_e32 v134, v136
	v_permlane32_swap_b32_e32 v135, v137
	v_permlane32_swap_b32_e32 v138, v140
	v_permlane32_swap_b32_e32 v139, v141
	v_permlane32_swap_b32_e32 v142, v144
	v_permlane32_swap_b32_e32 v143, v145
	ds_read_b64_tr_b16 v[156:157], v251 offset:512
	ds_read_b64_tr_b16 v[158:159], v251 offset:4608
	ds_read_b64_tr_b16 v[194:195], v251 offset:8704
	ds_read_b64_tr_b16 v[196:197], v251 offset:12800
	ds_read_b64_tr_b16 v[198:199], v251 offset:1024
	ds_read_b64_tr_b16 v[200:201], v251 offset:5120
	ds_read_b64_tr_b16 v[202:203], v251 offset:9216
	ds_read_b64_tr_b16 v[204:205], v251 offset:13312
	s_waitcnt lgkmcnt(8)
	v_mfma_f32_32x32x16_bf16 v[114:129], v[130:133], v[246:249], v[114:129]
	ds_read_b64_tr_b16 v[148:149], v251 offset:1536
	ds_read_b64_tr_b16 v[150:151], v251 offset:5632
	ds_read_b64_tr_b16 v[152:153], v251 offset:9728
	ds_read_b64_tr_b16 v[154:155], v251 offset:13824
	v_mfma_f32_32x32x16_bf16 v[114:129], v[134:137], v[252:255], v[114:129]
	s_waitcnt lgkmcnt(8)
	v_mfma_f32_32x32x16_bf16 v[98:113], v[130:133], v[156:159], v[98:113]
	ds_read_b64_tr_b16 v[206:207], v251 offset:2048
	ds_read_b64_tr_b16 v[208:209], v251 offset:6144
	ds_read_b64_tr_b16 v[244:245], v251 offset:10240
	ds_read_b64_tr_b16 v[246:247], v251 offset:14336
	v_mfma_f32_32x32x16_bf16 v[98:113], v[134:137], v[194:197], v[98:113]
	s_waitcnt lgkmcnt(8)
	v_mfma_f32_32x32x16_bf16 v[82:97], v[130:133], v[198:201], v[82:97]
	ds_read_b64_tr_b16 v[156:157], v251 offset:2560
	ds_read_b64_tr_b16 v[158:159], v251 offset:6656
	ds_read_b64_tr_b16 v[194:195], v251 offset:10752
	ds_read_b64_tr_b16 v[196:197], v251 offset:14848
	v_mfma_f32_32x32x16_bf16 v[82:97], v[134:137], v[202:205], v[82:97]
	s_waitcnt lgkmcnt(8)
	v_mfma_f32_32x32x16_bf16 v[66:81], v[130:133], v[148:151], v[66:81]
	ds_read_b64_tr_b16 v[198:199], v251 offset:3072
	ds_read_b64_tr_b16 v[200:201], v251 offset:7168
	ds_read_b64_tr_b16 v[202:203], v251 offset:11264
	ds_read_b64_tr_b16 v[204:205], v251 offset:15360
	v_mfma_f32_32x32x16_bf16 v[66:81], v[134:137], v[152:155], v[66:81]
	s_waitcnt lgkmcnt(8)
	v_mfma_f32_32x32x16_bf16 v[50:65], v[130:133], v[206:209], v[50:65]
	ds_read_b64_tr_b16 v[148:149], v251 offset:3584
	ds_read_b64_tr_b16 v[150:151], v251 offset:7680
	ds_read_b64_tr_b16 v[152:153], v251 offset:11776
	ds_read_b64_tr_b16 v[154:155], v251 offset:15872
	v_mfma_f32_32x32x16_bf16 v[50:65], v[134:137], v[244:247], v[50:65]
	s_waitcnt lgkmcnt(8)
	v_mfma_f32_32x32x16_bf16 v[34:49], v[130:133], v[156:159], v[34:49]
	ds_read_b64_tr_b16 v[206:207], v251 offset:16384
	ds_read_b64_tr_b16 v[208:209], v251 offset:20480
	ds_read_b64_tr_b16 v[244:245], v251 offset:24576
	ds_read_b64_tr_b16 v[246:247], v251 offset:28672
	v_mfma_f32_32x32x16_bf16 v[34:49], v[134:137], v[194:197], v[34:49]
	s_waitcnt lgkmcnt(8)
	v_mfma_f32_32x32x16_bf16 v[18:33], v[130:133], v[198:201], v[18:33]
	ds_read_b64_tr_b16 v[156:157], v251 offset:16896
	ds_read_b64_tr_b16 v[158:159], v251 offset:20992
	ds_read_b64_tr_b16 v[194:195], v251 offset:25088
	ds_read_b64_tr_b16 v[196:197], v251 offset:29184
	v_mfma_f32_32x32x16_bf16 v[18:33], v[134:137], v[202:205], v[18:33]
	s_waitcnt lgkmcnt(8)
	v_mfma_f32_32x32x16_bf16 v[2:17], v[130:133], v[148:151], v[2:17]
	ds_read_b64_tr_b16 v[198:199], v251 offset:17408
	ds_read_b64_tr_b16 v[200:201], v251 offset:21504
	ds_read_b64_tr_b16 v[202:203], v251 offset:25600
	ds_read_b64_tr_b16 v[204:205], v251 offset:29696
	v_mfma_f32_32x32x16_bf16 v[2:17], v[134:137], v[152:155], v[2:17]
	s_waitcnt lgkmcnt(8)
	v_mfma_f32_32x32x16_bf16 v[114:129], v[138:141], v[206:209], v[114:129]
	ds_read_b64_tr_b16 v[148:149], v251 offset:17920
	ds_read_b64_tr_b16 v[150:151], v251 offset:22016
	ds_read_b64_tr_b16 v[152:153], v251 offset:26112
	ds_read_b64_tr_b16 v[154:155], v251 offset:30208
	v_mfma_f32_32x32x16_bf16 v[114:129], v[142:145], v[244:247], v[114:129]
	s_waitcnt lgkmcnt(8)
	v_mfma_f32_32x32x16_bf16 v[98:113], v[138:141], v[156:159], v[98:113]
	ds_read_b64_tr_b16 v[206:207], v251 offset:18432
	ds_read_b64_tr_b16 v[208:209], v251 offset:22528
	ds_read_b64_tr_b16 v[244:245], v251 offset:26624
	ds_read_b64_tr_b16 v[246:247], v251 offset:30720
	v_mfma_f32_32x32x16_bf16 v[98:113], v[142:145], v[194:197], v[98:113]
	s_waitcnt lgkmcnt(8)
	v_mfma_f32_32x32x16_bf16 v[82:97], v[138:141], v[198:201], v[82:97]
	ds_read_b64_tr_b16 v[156:157], v251 offset:18944
	ds_read_b64_tr_b16 v[158:159], v251 offset:23040
	ds_read_b64_tr_b16 v[194:195], v251 offset:27136
	ds_read_b64_tr_b16 v[196:197], v251 offset:31232
	v_mfma_f32_32x32x16_bf16 v[82:97], v[142:145], v[202:205], v[82:97]
	s_waitcnt lgkmcnt(8)
	v_mfma_f32_32x32x16_bf16 v[66:81], v[138:141], v[148:151], v[66:81]
	ds_read_b64_tr_b16 v[198:199], v251 offset:19456
	ds_read_b64_tr_b16 v[200:201], v251 offset:23552
	ds_read_b64_tr_b16 v[202:203], v251 offset:27648
	ds_read_b64_tr_b16 v[204:205], v251 offset:31744
	v_mfma_f32_32x32x16_bf16 v[66:81], v[142:145], v[152:155], v[66:81]
	s_waitcnt lgkmcnt(8)
	v_mfma_f32_32x32x16_bf16 v[50:65], v[138:141], v[206:209], v[50:65]
	ds_read_b64_tr_b16 v[148:149], v251 offset:19968
	ds_read_b64_tr_b16 v[150:151], v251 offset:24064
	ds_read_b64_tr_b16 v[152:153], v251 offset:28160
	ds_read_b64_tr_b16 v[154:155], v251 offset:32256
	v_mfma_f32_32x32x16_bf16 v[50:65], v[142:145], v[244:247], v[50:65]
	s_waitcnt lgkmcnt(8)
	v_mfma_f32_32x32x16_bf16 v[34:49], v[138:141], v[156:159], v[34:49]
	v_mfma_f32_32x32x16_bf16 v[34:49], v[142:145], v[194:197], v[34:49]
	s_waitcnt lgkmcnt(4)
	v_mfma_f32_32x32x16_bf16 v[18:33], v[138:141], v[198:201], v[18:33]
	v_mfma_f32_32x32x16_bf16 v[18:33], v[142:145], v[202:205], v[18:33]
	s_waitcnt vmcnt(0) lgkmcnt(0)
	s_barrier
; #define SBAR() __builtin_amdgcn_sched_barrier(0)
; __device__ __forceinline__ int crow(int r, int hi) { return (r & 3) + 8 * (r >> 2) + 4 * hi; }
; __device__ __forceinline__ void body(const bf16_t* __restrict__ Qb, const bf16_t* __restrict__ Kh, const bf16_t* __restrict__ Vh, bf16_t* __restrict__ Ob, int seq, char* lds) {
;     ...
;   for (int j = 0; j < NT; ++j) {
;     const int b = j & 1;
;     f32x16 p0, p1; float mn, al; bf16x8 pa0, pa1, pa2, pa3;
;     if (j + 1 < NT) STAGE(b ^ 1, (j + 1) * KVBLK);
;     SBAR(); qkt(p0, p1, K_lds + b * SK, qr, r32, hi);
;     partialSM(p0, p1, m_reg, mn, al);
;     if (__any(al < 1.f)) { if (hi == 0) al_l[r32] = al; asm volatile("s_waitcnt lgkmcnt(0)" ::: "memory");
; #pragma unroll
;       for (int d = 0; d < 8; ++d)
; #pragma unroll
;         for (int r = 0; r < 16; ++r) o[d][r] *= al_l[crow(r, hi)]; }
;     finishSM(p0, p1, al, l_reg, pa0, pa1, pa2, pa3); SBAR();
;     const int vb = vb0 + b * SV;
;     pv_all(o, vb, pa0, pa1, pa2, pa3);
;     asm volatile("s_waitcnt vmcnt(0) lgkmcnt(0)" ::: "memory"); __builtin_amdgcn_s_barrier(); asm volatile("" ::: "memory");
	s_and_b32 s8, s29, 1
	s_lshl_b32 s8, s8, 14
	s_add_i32 s8, s8, 0x10010
	v_add3_u32 v1, s8, v233, v213
	ds_read_b128 v[194:197], v1
	ds_read_b128 v[198:201], v1 offset:8192
	v_add3_u32 v1, s8, v234, v213
	ds_read_b128 v[202:205], v1
	ds_read_b128 v[206:209], v1 offset:8192
	v_add3_u32 v1, s8, v235, v213
	ds_read_b128 v[246:249], v1
	ds_read_b128 v[252:255], v1 offset:8192
	s_cmp_eq_u32 s24, s29
	v_mfma_f32_32x32x16_bf16 v[2:17], v[138:141], v[148:151], v[2:17]
	v_mfma_f32_32x32x16_bf16 v[2:17], v[142:145], v[152:155], v[2:17]
	s_cbranch_scc1 .LBB0_626
	v_mov_b32_e32 v244, v146
	s_branch .LBB0_616

; __global__ void __launch_bounds__(NTHREADS) mega(Params p_arg) {
	.amdhsa_kernel _Z4mega6Params
		.amdhsa_group_segment_fixed_size 16
		.amdhsa_private_segment_fixed_size 0
		.amdhsa_kernarg_size 528
		.amdhsa_user_sgpr_count 2
		.amdhsa_user_sgpr_dispatch_ptr 0
		.amdhsa_user_sgpr_queue_ptr 0
		.amdhsa_user_sgpr_kernarg_segment_ptr 1
		.amdhsa_user_sgpr_dispatch_id 0
		.amdhsa_user_sgpr_kernarg_preload_length 0
		.amdhsa_user_sgpr_kernarg_preload_offset 0
		.amdhsa_user_sgpr_private_segment_size 0
		.amdhsa_uses_dynamic_stack 0
		.amdhsa_enable_private_segment 0
		.amdhsa_system_sgpr_workgroup_id_x 1
		.amdhsa_system_sgpr_workgroup_id_y 0
		.amdhsa_system_sgpr_workgroup_id_z 0
		.amdhsa_system_sgpr_workgroup_info 0
		.amdhsa_system_vgpr_workitem_id 2
		.amdhsa_next_free_vgpr 256
		.amdhsa_next_free_sgpr 102
		.amdhsa_accum_offset 256
		.amdhsa_reserve_vcc 1
		.amdhsa_float_round_mode_32 0
		.amdhsa_float_round_mode_16_64 0
		.amdhsa_float_denorm_mode_32 3
		.amdhsa_float_denorm_mode_16_64 3
		.amdhsa_dx10_clamp 1
		.amdhsa_ieee_mode 1
		.amdhsa_fp16_overflow 0
		.amdhsa_tg_split 0
		.amdhsa_exception_fp_ieee_invalid_op 0
		.amdhsa_exception_fp_denorm_src 0
		.amdhsa_exception_fp_ieee_div_zero 0
		.amdhsa_exception_fp_ieee_overflow 0
		.amdhsa_exception_fp_ieee_underflow 0
		.amdhsa_exception_fp_ieee_inexact 0
		.amdhsa_exception_int_div_zero 0
	.end_amdhsa_kernel

; __global__ void __launch_bounds__(NTHREADS) mega(Params p_arg) {
amdhsa.kernels:
  - .agpr_count:     0
    .args:
      - .offset:         0
        .size:           272
        .value_kind:     by_value
      - .offset:         272
        .size:           4
        .value_kind:     hidden_block_count_x
      - .offset:         276
        .size:           4
        .value_kind:     hidden_block_count_y
      - .offset:         280
        .size:           4
        .value_kind:     hidden_block_count_z
      - .offset:         284
        .size:           2
        .value_kind:     hidden_group_size_x
      - .offset:         286
        .size:           2
        .value_kind:     hidden_group_size_y
      - .offset:         288
        .size:           2
        .value_kind:     hidden_group_size_z
      - .offset:         290
        .size:           2
        .value_kind:     hidden_remainder_x
      - .offset:         292
        .size:           2
        .value_kind:     hidden_remainder_y
      - .offset:         294
        .size:           2
        .value_kind:     hidden_remainder_z
      - .offset:         312
        .size:           8
        .value_kind:     hidden_global_offset_x
      - .offset:         320
        .size:           8
        .value_kind:     hidden_global_offset_y
      - .offset:         328
        .size:           8
        .value_kind:     hidden_global_offset_z
      - .offset:         336
        .size:           2
        .value_kind:     hidden_grid_dims
      - .offset:         360
        .size:           8
        .value_kind:     hidden_multigrid_sync_arg
      - .offset:         392
        .size:           4
        .value_kind:     hidden_dynamic_lds_size
    .group_segment_fixed_size: 16
    .kernarg_segment_align: 8
    .kernarg_segment_size: 528
    .language:       OpenCL C
    .language_version:
      - 2
      - 0
    .max_flat_workgroup_size: 512
    .name:           _Z4mega6Params
    .private_segment_fixed_size: 0
    .sgpr_count:     108
    .sgpr_spill_count: 23
    .symbol:         _Z4mega6Params.kd
    .uniform_work_group_size: 1
    .uses_dynamic_stack: false
    .vgpr_count:     256
    .vgpr_spill_count: 0
    .wavefront_size: 64
